# P2 kv epilogue: all eight sum-of-squares row loads issued up front into free fragment registers behind one wait; stores get dedicated data registers
# baseline (speedup 1.0000x reference)
.LBB0_357:
	v_lshl_add_u32 v146, s80, 8, v148
	v_lshlrev_b32_e32 v144, 2, v146
	v_ashrrev_i32_e32 v145, 31, v144
	v_lshl_add_u64 v[144:145], v[144:145], 2, s[40:41]
	v_mov_b32_e32 v240, v144
	v_mov_b32_e32 v241, v145
	global_load_dwordx4 v[188:191], v[240:241], off
	global_load_dwordx4 v[192:195], v[240:241], off offset:256
	global_load_dwordx4 v[196:199], v[240:241], off offset:512
	global_load_dwordx4 v[200:203], v[240:241], off offset:768
	global_load_dwordx4 v[204:207], v[240:241], off offset:2048
	global_load_dwordx4 v[208:211], v[240:241], off offset:2304
	global_load_dwordx4 v[212:215], v[240:241], off offset:2560
	global_load_dwordx4 v[216:219], v[240:241], off offset:2816
	v_ashrrev_i32_e32 v147, 31, v146
	v_lshlrev_b64 v[162:163], 11, v[146:147]
	v_or_b32_e32 v160, 16, v146
	v_lshlrev_b32_e32 v164, 2, v160
	v_ashrrev_i32_e32 v165, 31, v164
	v_lshl_or_b32 v144, s81, 8, v150
	v_ashrrev_i32_e32 v145, 31, v144
	v_lshlrev_b64 v[144:145], 1, v[144:145]
	s_waitcnt vmcnt(0)
	v_mov_b32_e32 v156, v188
	v_mov_b32_e32 v157, v189
	v_mov_b32_e32 v158, v190
	v_mov_b32_e32 v159, v191
	v_mov_b32_e32 v166, v157
	v_mov_b32_e32 v167, v158
	v_mov_b32_e32 v157, v159
	v_pk_add_f32 v[156:157], v[166:167], v[156:157]
	s_nop 0
	v_add_f32_e32 v147, v156, v157
	v_fmamk_f32 v147, v147, 0x3c000000, v154
	v_mul_f32_e32 v156, 0x4f800000, v147
	v_cmp_gt_f32_e32 vcc, s77, v147
	s_nop 1
	v_cndmask_b32_e32 v147, v147, v156, vcc
	v_sqrt_f32_e32 v158, v147
	v_lshl_add_u64 v[156:157], s[44:45], 0, v[162:163]
	v_lshl_add_u64 v[156:157], v[156:157], 0, v[144:145]
	v_add_u32_e32 v159, -1, v158
	v_add_u32_e32 v161, 1, v158
	v_fma_f32 v162, -v159, v158, v147
	v_fma_f32 v163, -v161, v158, v147
	v_cmp_ge_f32_e64 s[6:7], 0, v162
	s_nop 1
	v_cndmask_b32_e64 v158, v158, v159, s[6:7]
	v_cmp_lt_f32_e64 s[6:7], 0, v163
	s_nop 1
	v_cndmask_b32_e64 v158, v158, v161, s[6:7]
	v_mul_f32_e32 v159, 0x37800000, v158
	v_cndmask_b32_e32 v158, v158, v159, vcc
	v_cmp_class_f32_e32 vcc, v147, v155
	s_nop 1
	v_cndmask_b32_e32 v147, v158, v147, vcc
	v_div_scale_f32 v161, s[6:7], v147, v147, 1.0
	v_rcp_f32_e32 v162, v161
	v_lshl_add_u64 v[158:159], v[164:165], 2, s[40:41]
	v_div_scale_f32 v163, vcc, 1.0, v147, 1.0
	v_fma_f32 v164, -v161, v162, 1.0
	v_fmac_f32_e32 v162, v164, v162
	v_mul_f32_e32 v164, v163, v162
	v_fma_f32 v165, -v161, v164, v163
	v_fmac_f32_e32 v164, v165, v162
	v_fma_f32 v161, -v161, v164, v163
	v_div_fmas_f32 v161, v161, v162, v164
	v_div_fixup_f32 v162, v161, v147, 1.0
	v_pk_mul_f32 v[126:127], v[126:127], v[162:163] op_sel_hi:[1,0]
	v_pk_mul_f32 v[124:125], v[124:125], v[162:163] op_sel_hi:[1,0]
	v_pk_mul_f32 v[122:123], v[122:123], v[162:163] op_sel_hi:[1,0]
	v_pk_mul_f32 v[120:121], v[120:121], v[162:163] op_sel_hi:[1,0]
	v_pk_mul_f32 v[118:119], v[118:119], v[162:163] op_sel_hi:[1,0]
	v_pk_mul_f32 v[116:117], v[116:117], v[162:163] op_sel_hi:[1,0]
	v_pk_mul_f32 v[164:165], v[114:115], v[162:163] op_sel_hi:[1,0]
	v_pk_mul_f32 v[162:163], v[112:113], v[162:163] op_sel_hi:[1,0]
	v_cvt_pk_bf16_f32 v176, v124, v125
	v_cvt_pk_bf16_f32 v177, v126, v127
	v_cvt_pk_bf16_f32 v178, v120, v121
	v_cvt_pk_bf16_f32 v179, v122, v123
	global_store_dwordx4 v[156:157], v[176:179], off
	v_ashrrev_i32_e32 v161, 31, v160
	v_lshlrev_b64 v[120:121], 11, v[160:161]
	v_cvt_pk_bf16_f32 v168, v116, v117
	v_cvt_pk_bf16_f32 v169, v118, v119
	v_cvt_pk_bf16_f32 v170, v162, v163
	v_cvt_pk_bf16_f32 v171, v164, v165
	global_store_dwordx4 v[156:157], v[168:171], off offset:256
	v_or_b32_e32 v116, 32, v146
	v_lshlrev_b32_e32 v118, 2, v116
	v_ashrrev_i32_e32 v119, 31, v118
	s_nop 7
	v_mov_b32_e32 v112, v192
	v_mov_b32_e32 v113, v193
	v_mov_b32_e32 v114, v194
	v_mov_b32_e32 v115, v195
	v_mov_b32_e32 v122, v113
	v_mov_b32_e32 v123, v114
	v_mov_b32_e32 v113, v115
	v_pk_add_f32 v[112:113], v[122:123], v[112:113]
	v_lshl_add_u64 v[114:115], v[118:119], 2, s[40:41]
	v_add_f32_e32 v112, v112, v113
	v_fmamk_f32 v112, v112, 0x3c000000, v154
	v_mul_f32_e32 v113, 0x4f800000, v112
	v_cmp_gt_f32_e32 vcc, s77, v112
	s_nop 1
	v_cndmask_b32_e32 v117, v112, v113, vcc
	v_sqrt_f32_e32 v122, v117
	v_lshl_add_u64 v[112:113], s[44:45], 0, v[120:121]
	v_lshl_add_u64 v[112:113], v[112:113], 0, v[144:145]
	v_add_u32_e32 v118, -1, v122
	v_add_u32_e32 v119, 1, v122
	v_fma_f32 v120, -v118, v122, v117
	v_fma_f32 v121, -v119, v122, v117
	v_cmp_ge_f32_e64 s[6:7], 0, v120
	s_nop 1
	v_cndmask_b32_e64 v118, v122, v118, s[6:7]
	v_cmp_lt_f32_e64 s[6:7], 0, v121
	s_nop 1
	v_cndmask_b32_e64 v118, v118, v119, s[6:7]
	v_mul_f32_e32 v119, 0x37800000, v118
	v_cndmask_b32_e32 v118, v118, v119, vcc
	v_cmp_class_f32_e32 vcc, v117, v155
	s_nop 1
	v_cndmask_b32_e32 v117, v118, v117, vcc
	v_div_scale_f32 v118, s[6:7], v117, v117, 1.0
	v_rcp_f32_e32 v119, v118
	v_div_scale_f32 v120, vcc, 1.0, v117, 1.0
	v_fma_f32 v121, -v118, v119, 1.0
	v_fmac_f32_e32 v119, v121, v119
	v_mul_f32_e32 v121, v120, v119
	v_fma_f32 v122, -v118, v121, v120
	v_fmac_f32_e32 v121, v122, v119
	v_fma_f32 v118, -v118, v121, v120
	v_div_fmas_f32 v118, v118, v119, v121
	v_div_fixup_f32 v118, v118, v117, 1.0
	v_pk_mul_f32 v[110:111], v[110:111], v[118:119] op_sel_hi:[1,0]
	v_pk_mul_f32 v[108:109], v[108:109], v[118:119] op_sel_hi:[1,0]
	v_pk_mul_f32 v[106:107], v[106:107], v[118:119] op_sel_hi:[1,0]
	v_pk_mul_f32 v[104:105], v[104:105], v[118:119] op_sel_hi:[1,0]
	v_pk_mul_f32 v[102:103], v[102:103], v[118:119] op_sel_hi:[1,0]
	v_pk_mul_f32 v[100:101], v[100:101], v[118:119] op_sel_hi:[1,0]
	v_pk_mul_f32 v[120:121], v[98:99], v[118:119] op_sel_hi:[1,0]
	v_pk_mul_f32 v[118:119], v[96:97], v[118:119] op_sel_hi:[1,0]
	v_cvt_pk_bf16_f32 v180, v108, v109
	v_cvt_pk_bf16_f32 v181, v110, v111
	v_cvt_pk_bf16_f32 v182, v104, v105
	v_cvt_pk_bf16_f32 v183, v106, v107
	global_store_dwordx4 v[112:113], v[180:183], off
	v_ashrrev_i32_e32 v117, 31, v116
	v_lshlrev_b64 v[104:105], 11, v[116:117]
	v_cvt_pk_bf16_f32 v172, v100, v101
	v_cvt_pk_bf16_f32 v173, v102, v103
	v_cvt_pk_bf16_f32 v174, v118, v119
	v_cvt_pk_bf16_f32 v175, v120, v121
	global_store_dwordx4 v[112:113], v[172:175], off offset:256
	v_or_b32_e32 v100, 48, v146
	v_lshlrev_b32_e32 v102, 2, v100
	v_ashrrev_i32_e32 v103, 31, v102
	s_nop 7
	v_mov_b32_e32 v96, v196
	v_mov_b32_e32 v97, v197
	v_mov_b32_e32 v98, v198
	v_mov_b32_e32 v99, v199
	v_mov_b32_e32 v106, v97
	v_mov_b32_e32 v107, v98
	v_mov_b32_e32 v97, v99
	v_pk_add_f32 v[96:97], v[106:107], v[96:97]
	v_lshl_add_u64 v[98:99], v[102:103], 2, s[40:41]
	v_add_f32_e32 v96, v96, v97
	v_fmamk_f32 v96, v96, 0x3c000000, v154
	v_mul_f32_e32 v97, 0x4f800000, v96
	v_cmp_gt_f32_e32 vcc, s77, v96
	s_nop 1
	v_cndmask_b32_e32 v101, v96, v97, vcc
	v_sqrt_f32_e32 v106, v101
	v_lshl_add_u64 v[96:97], s[44:45], 0, v[104:105]
	v_lshl_add_u64 v[96:97], v[96:97], 0, v[144:145]
	v_add_u32_e32 v102, -1, v106
	v_add_u32_e32 v103, 1, v106
	v_fma_f32 v104, -v102, v106, v101
	v_fma_f32 v105, -v103, v106, v101
	v_cmp_ge_f32_e64 s[6:7], 0, v104
	s_nop 1
	v_cndmask_b32_e64 v102, v106, v102, s[6:7]
	v_cmp_lt_f32_e64 s[6:7], 0, v105
	s_nop 1
	v_cndmask_b32_e64 v102, v102, v103, s[6:7]
	v_mul_f32_e32 v103, 0x37800000, v102
	v_cndmask_b32_e32 v102, v102, v103, vcc
	v_cmp_class_f32_e32 vcc, v101, v155
	s_nop 1
	v_cndmask_b32_e32 v101, v102, v101, vcc
	v_div_scale_f32 v102, s[6:7], v101, v101, 1.0
	v_rcp_f32_e32 v103, v102
	v_div_scale_f32 v104, vcc, 1.0, v101, 1.0
	v_fma_f32 v105, -v102, v103, 1.0
	v_fmac_f32_e32 v103, v105, v103
	v_mul_f32_e32 v105, v104, v103
	v_fma_f32 v106, -v102, v105, v104
	v_fmac_f32_e32 v105, v106, v103
	v_fma_f32 v102, -v102, v105, v104
	v_div_fmas_f32 v102, v102, v103, v105
	v_div_fixup_f32 v102, v102, v101, 1.0
	v_pk_mul_f32 v[94:95], v[94:95], v[102:103] op_sel_hi:[1,0]
	v_pk_mul_f32 v[92:93], v[92:93], v[102:103] op_sel_hi:[1,0]
	v_pk_mul_f32 v[90:91], v[90:91], v[102:103] op_sel_hi:[1,0]
	v_pk_mul_f32 v[88:89], v[88:89], v[102:103] op_sel_hi:[1,0]
	v_pk_mul_f32 v[86:87], v[86:87], v[102:103] op_sel_hi:[1,0]
	v_pk_mul_f32 v[84:85], v[84:85], v[102:103] op_sel_hi:[1,0]
	v_pk_mul_f32 v[104:105], v[82:83], v[102:103] op_sel_hi:[1,0]
	v_pk_mul_f32 v[102:103], v[80:81], v[102:103] op_sel_hi:[1,0]
	v_cvt_pk_bf16_f32 v176, v92, v93
	v_cvt_pk_bf16_f32 v177, v94, v95
	v_cvt_pk_bf16_f32 v178, v88, v89
	v_cvt_pk_bf16_f32 v179, v90, v91
	global_store_dwordx4 v[96:97], v[176:179], off
	v_ashrrev_i32_e32 v101, 31, v100
	v_lshlrev_b64 v[88:89], 11, v[100:101]
	v_cvt_pk_bf16_f32 v168, v84, v85
	v_cvt_pk_bf16_f32 v169, v86, v87
	v_cvt_pk_bf16_f32 v170, v102, v103
	v_cvt_pk_bf16_f32 v171, v104, v105
	global_store_dwordx4 v[96:97], v[168:171], off offset:256
	v_add_u32_e32 v84, 0x80, v146
	v_lshlrev_b32_e32 v86, 2, v84
	v_ashrrev_i32_e32 v87, 31, v86
	s_nop 7
	v_mov_b32_e32 v80, v200
	v_mov_b32_e32 v81, v201
	v_mov_b32_e32 v82, v202
	v_mov_b32_e32 v83, v203
	v_mov_b32_e32 v90, v81
	v_mov_b32_e32 v91, v82
	v_mov_b32_e32 v81, v83
	v_pk_add_f32 v[80:81], v[90:91], v[80:81]
	v_lshl_add_u64 v[82:83], v[86:87], 2, s[40:41]
	v_add_f32_e32 v80, v80, v81
	v_fmamk_f32 v80, v80, 0x3c000000, v154
	v_mul_f32_e32 v81, 0x4f800000, v80
	v_cmp_gt_f32_e32 vcc, s77, v80
	s_nop 1
	v_cndmask_b32_e32 v85, v80, v81, vcc
	v_sqrt_f32_e32 v90, v85
	v_lshl_add_u64 v[80:81], s[44:45], 0, v[88:89]
	v_lshl_add_u64 v[80:81], v[80:81], 0, v[144:145]
	v_add_u32_e32 v86, -1, v90
	v_add_u32_e32 v87, 1, v90
	v_fma_f32 v88, -v86, v90, v85
	v_fma_f32 v89, -v87, v90, v85
	v_cmp_ge_f32_e64 s[6:7], 0, v88
	s_nop 1
	v_cndmask_b32_e64 v86, v90, v86, s[6:7]
	v_cmp_lt_f32_e64 s[6:7], 0, v89
	s_nop 1
	v_cndmask_b32_e64 v86, v86, v87, s[6:7]
	v_mul_f32_e32 v87, 0x37800000, v86
	v_cndmask_b32_e32 v86, v86, v87, vcc
	v_cmp_class_f32_e32 vcc, v85, v155
	s_nop 1
	v_cndmask_b32_e32 v85, v86, v85, vcc
	v_div_scale_f32 v86, s[6:7], v85, v85, 1.0
	v_rcp_f32_e32 v87, v86
	v_div_scale_f32 v88, vcc, 1.0, v85, 1.0
	v_fma_f32 v89, -v86, v87, 1.0
	v_fmac_f32_e32 v87, v89, v87
	v_mul_f32_e32 v89, v88, v87
	v_fma_f32 v90, -v86, v89, v88
	v_fmac_f32_e32 v89, v90, v87
	v_fma_f32 v86, -v86, v89, v88
	v_div_fmas_f32 v86, v86, v87, v89
	v_div_fixup_f32 v86, v86, v85, 1.0
	v_pk_mul_f32 v[78:79], v[78:79], v[86:87] op_sel_hi:[1,0]
	v_pk_mul_f32 v[76:77], v[76:77], v[86:87] op_sel_hi:[1,0]
	v_pk_mul_f32 v[74:75], v[74:75], v[86:87] op_sel_hi:[1,0]
	v_pk_mul_f32 v[72:73], v[72:73], v[86:87] op_sel_hi:[1,0]
	v_pk_mul_f32 v[70:71], v[70:71], v[86:87] op_sel_hi:[1,0]
	v_pk_mul_f32 v[68:69], v[68:69], v[86:87] op_sel_hi:[1,0]
	v_pk_mul_f32 v[88:89], v[66:67], v[86:87] op_sel_hi:[1,0]
	v_pk_mul_f32 v[86:87], v[64:65], v[86:87] op_sel_hi:[1,0]
	v_cvt_pk_bf16_f32 v180, v76, v77
	v_cvt_pk_bf16_f32 v181, v78, v79
	v_cvt_pk_bf16_f32 v182, v72, v73
	v_cvt_pk_bf16_f32 v183, v74, v75
	global_store_dwordx4 v[80:81], v[180:183], off
	v_ashrrev_i32_e32 v85, 31, v84
	v_lshlrev_b64 v[72:73], 11, v[84:85]
	v_cvt_pk_bf16_f32 v172, v68, v69
	v_cvt_pk_bf16_f32 v173, v70, v71
	v_cvt_pk_bf16_f32 v174, v86, v87
	v_cvt_pk_bf16_f32 v175, v88, v89
	global_store_dwordx4 v[80:81], v[172:175], off offset:256
	v_add_u32_e32 v68, 0x90, v146
	v_lshlrev_b32_e32 v70, 2, v68
	v_ashrrev_i32_e32 v71, 31, v70
	s_nop 7
	v_mov_b32_e32 v64, v204
	v_mov_b32_e32 v65, v205
	v_mov_b32_e32 v66, v206
	v_mov_b32_e32 v67, v207
	v_mov_b32_e32 v74, v65
	v_mov_b32_e32 v75, v66
	v_mov_b32_e32 v65, v67
	v_pk_add_f32 v[64:65], v[74:75], v[64:65]
	v_lshl_add_u64 v[66:67], v[70:71], 2, s[40:41]
	v_add_f32_e32 v64, v64, v65
	v_fmamk_f32 v64, v64, 0x3c000000, v154
	v_mul_f32_e32 v65, 0x4f800000, v64
	v_cmp_gt_f32_e32 vcc, s77, v64
	s_nop 1
	v_cndmask_b32_e32 v69, v64, v65, vcc
	v_sqrt_f32_e32 v74, v69
	v_lshl_add_u64 v[64:65], s[44:45], 0, v[72:73]
	v_lshl_add_u64 v[64:65], v[64:65], 0, v[144:145]
	v_add_u32_e32 v70, -1, v74
	v_add_u32_e32 v71, 1, v74
	v_fma_f32 v72, -v70, v74, v69
	v_fma_f32 v73, -v71, v74, v69
	v_cmp_ge_f32_e64 s[6:7], 0, v72
	s_nop 1
	v_cndmask_b32_e64 v70, v74, v70, s[6:7]
	v_cmp_lt_f32_e64 s[6:7], 0, v73
	s_nop 1
	v_cndmask_b32_e64 v70, v70, v71, s[6:7]
	v_mul_f32_e32 v71, 0x37800000, v70
	v_cndmask_b32_e32 v70, v70, v71, vcc
	v_cmp_class_f32_e32 vcc, v69, v155
	s_nop 1
	v_cndmask_b32_e32 v69, v70, v69, vcc
	v_div_scale_f32 v70, s[6:7], v69, v69, 1.0
	v_rcp_f32_e32 v71, v70
	v_div_scale_f32 v72, vcc, 1.0, v69, 1.0
	v_fma_f32 v73, -v70, v71, 1.0
	v_fmac_f32_e32 v71, v73, v71
	v_mul_f32_e32 v73, v72, v71
	v_fma_f32 v74, -v70, v73, v72
	v_fmac_f32_e32 v73, v74, v71
	v_fma_f32 v70, -v70, v73, v72
	v_div_fmas_f32 v70, v70, v71, v73
	v_div_fixup_f32 v70, v70, v69, 1.0
	v_pk_mul_f32 v[62:63], v[62:63], v[70:71] op_sel_hi:[1,0]
	v_pk_mul_f32 v[60:61], v[60:61], v[70:71] op_sel_hi:[1,0]
	v_pk_mul_f32 v[58:59], v[58:59], v[70:71] op_sel_hi:[1,0]
	v_pk_mul_f32 v[56:57], v[56:57], v[70:71] op_sel_hi:[1,0]
	v_pk_mul_f32 v[54:55], v[54:55], v[70:71] op_sel_hi:[1,0]
	v_pk_mul_f32 v[52:53], v[52:53], v[70:71] op_sel_hi:[1,0]
	v_pk_mul_f32 v[72:73], v[50:51], v[70:71] op_sel_hi:[1,0]
	v_pk_mul_f32 v[70:71], v[48:49], v[70:71] op_sel_hi:[1,0]
	v_cvt_pk_bf16_f32 v176, v60, v61
	v_cvt_pk_bf16_f32 v177, v62, v63
	v_cvt_pk_bf16_f32 v178, v56, v57
	v_cvt_pk_bf16_f32 v179, v58, v59
	global_store_dwordx4 v[64:65], v[176:179], off
	v_ashrrev_i32_e32 v69, 31, v68
	v_lshlrev_b64 v[56:57], 11, v[68:69]
	v_cvt_pk_bf16_f32 v168, v52, v53
	v_cvt_pk_bf16_f32 v169, v54, v55
	v_cvt_pk_bf16_f32 v170, v70, v71
	v_cvt_pk_bf16_f32 v171, v72, v73
	global_store_dwordx4 v[64:65], v[168:171], off offset:256
	v_add_u32_e32 v52, 0xa0, v146
	v_lshlrev_b32_e32 v54, 2, v52
	v_ashrrev_i32_e32 v55, 31, v54
	s_nop 7
	v_mov_b32_e32 v48, v208
	v_mov_b32_e32 v49, v209
	v_mov_b32_e32 v50, v210
	v_mov_b32_e32 v51, v211
	v_mov_b32_e32 v58, v49
	v_mov_b32_e32 v59, v50
	v_mov_b32_e32 v49, v51
	v_pk_add_f32 v[48:49], v[58:59], v[48:49]
	v_lshl_add_u64 v[50:51], v[54:55], 2, s[40:41]
	v_add_f32_e32 v48, v48, v49
	v_fmamk_f32 v48, v48, 0x3c000000, v154
	v_mul_f32_e32 v49, 0x4f800000, v48
	v_cmp_gt_f32_e32 vcc, s77, v48
	s_nop 1
	v_cndmask_b32_e32 v53, v48, v49, vcc
	v_sqrt_f32_e32 v58, v53
	v_lshl_add_u64 v[48:49], s[44:45], 0, v[56:57]
	v_lshl_add_u64 v[48:49], v[48:49], 0, v[144:145]
	v_add_u32_e32 v54, -1, v58
	v_add_u32_e32 v55, 1, v58
	v_fma_f32 v56, -v54, v58, v53
	v_fma_f32 v57, -v55, v58, v53
	v_cmp_ge_f32_e64 s[6:7], 0, v56
	s_nop 1
	v_cndmask_b32_e64 v54, v58, v54, s[6:7]
	v_cmp_lt_f32_e64 s[6:7], 0, v57
	s_nop 1
	v_cndmask_b32_e64 v54, v54, v55, s[6:7]
	v_mul_f32_e32 v55, 0x37800000, v54
	v_cndmask_b32_e32 v54, v54, v55, vcc
	v_cmp_class_f32_e32 vcc, v53, v155
	s_nop 1
	v_cndmask_b32_e32 v53, v54, v53, vcc
	v_div_scale_f32 v54, s[6:7], v53, v53, 1.0
	v_rcp_f32_e32 v55, v54
	v_div_scale_f32 v56, vcc, 1.0, v53, 1.0
	v_fma_f32 v57, -v54, v55, 1.0
	v_fmac_f32_e32 v55, v57, v55
	v_mul_f32_e32 v57, v56, v55
	v_fma_f32 v58, -v54, v57, v56
	v_fmac_f32_e32 v57, v58, v55
	v_fma_f32 v54, -v54, v57, v56
	v_div_fmas_f32 v54, v54, v55, v57
	v_div_fixup_f32 v54, v54, v53, 1.0
	v_pk_mul_f32 v[46:47], v[46:47], v[54:55] op_sel_hi:[1,0]
	v_pk_mul_f32 v[44:45], v[44:45], v[54:55] op_sel_hi:[1,0]
	v_pk_mul_f32 v[42:43], v[42:43], v[54:55] op_sel_hi:[1,0]
	v_pk_mul_f32 v[40:41], v[40:41], v[54:55] op_sel_hi:[1,0]
	v_pk_mul_f32 v[38:39], v[38:39], v[54:55] op_sel_hi:[1,0]
	v_pk_mul_f32 v[36:37], v[36:37], v[54:55] op_sel_hi:[1,0]
	v_pk_mul_f32 v[56:57], v[34:35], v[54:55] op_sel_hi:[1,0]
	v_pk_mul_f32 v[54:55], v[32:33], v[54:55] op_sel_hi:[1,0]
	v_cvt_pk_bf16_f32 v180, v44, v45
	v_cvt_pk_bf16_f32 v181, v46, v47
	v_cvt_pk_bf16_f32 v182, v40, v41
	v_cvt_pk_bf16_f32 v183, v42, v43
	global_store_dwordx4 v[48:49], v[180:183], off
	v_ashrrev_i32_e32 v53, 31, v52
	v_lshlrev_b64 v[40:41], 11, v[52:53]
	v_cvt_pk_bf16_f32 v172, v36, v37
	v_cvt_pk_bf16_f32 v173, v38, v39
	v_cvt_pk_bf16_f32 v174, v54, v55
	v_cvt_pk_bf16_f32 v175, v56, v57
	global_store_dwordx4 v[48:49], v[172:175], off offset:256
	v_add_u32_e32 v36, 0xb0, v146
	v_lshlrev_b32_e32 v38, 2, v36
	v_ashrrev_i32_e32 v39, 31, v38
	s_nop 7
	v_mov_b32_e32 v32, v212
	v_mov_b32_e32 v33, v213
	v_mov_b32_e32 v34, v214
	v_mov_b32_e32 v35, v215
	v_mov_b32_e32 v42, v33
	v_mov_b32_e32 v43, v34
	v_mov_b32_e32 v33, v35
	v_pk_add_f32 v[32:33], v[42:43], v[32:33]
	v_lshl_add_u64 v[34:35], v[38:39], 2, s[40:41]
	v_add_f32_e32 v32, v32, v33
	v_fmamk_f32 v32, v32, 0x3c000000, v154
	v_mul_f32_e32 v33, 0x4f800000, v32
	v_cmp_gt_f32_e32 vcc, s77, v32
	s_nop 1
	v_cndmask_b32_e32 v37, v32, v33, vcc
	v_sqrt_f32_e32 v42, v37
	v_lshl_add_u64 v[32:33], s[44:45], 0, v[40:41]
	v_lshl_add_u64 v[32:33], v[32:33], 0, v[144:145]
	v_add_u32_e32 v38, -1, v42
	v_add_u32_e32 v39, 1, v42
	v_fma_f32 v40, -v38, v42, v37
	v_fma_f32 v41, -v39, v42, v37
	v_cmp_ge_f32_e64 s[6:7], 0, v40
	s_nop 1
	v_cndmask_b32_e64 v38, v42, v38, s[6:7]
	v_cmp_lt_f32_e64 s[6:7], 0, v41
	s_nop 1
	v_cndmask_b32_e64 v38, v38, v39, s[6:7]
	v_mul_f32_e32 v39, 0x37800000, v38
	v_cndmask_b32_e32 v38, v38, v39, vcc
	v_cmp_class_f32_e32 vcc, v37, v155
	s_nop 1
	v_cndmask_b32_e32 v37, v38, v37, vcc
	v_div_scale_f32 v38, s[6:7], v37, v37, 1.0
	v_rcp_f32_e32 v39, v38
	v_div_scale_f32 v40, vcc, 1.0, v37, 1.0
	v_fma_f32 v41, -v38, v39, 1.0
	v_fmac_f32_e32 v39, v41, v39
	v_mul_f32_e32 v41, v40, v39
	v_fma_f32 v42, -v38, v41, v40
	v_fmac_f32_e32 v41, v42, v39
	v_fma_f32 v38, -v38, v41, v40
	v_div_fmas_f32 v38, v38, v39, v41
	v_div_fixup_f32 v38, v38, v37, 1.0
	v_pk_mul_f32 v[30:31], v[30:31], v[38:39] op_sel_hi:[1,0]
	v_pk_mul_f32 v[28:29], v[28:29], v[38:39] op_sel_hi:[1,0]
	v_pk_mul_f32 v[26:27], v[26:27], v[38:39] op_sel_hi:[1,0]
	v_pk_mul_f32 v[24:25], v[24:25], v[38:39] op_sel_hi:[1,0]
	v_pk_mul_f32 v[22:23], v[22:23], v[38:39] op_sel_hi:[1,0]
	v_pk_mul_f32 v[20:21], v[20:21], v[38:39] op_sel_hi:[1,0]
	v_pk_mul_f32 v[40:41], v[18:19], v[38:39] op_sel_hi:[1,0]
	v_pk_mul_f32 v[38:39], v[16:17], v[38:39] op_sel_hi:[1,0]
	v_cvt_pk_bf16_f32 v176, v28, v29
	v_cvt_pk_bf16_f32 v177, v30, v31
	v_cvt_pk_bf16_f32 v178, v24, v25
	v_cvt_pk_bf16_f32 v179, v26, v27
	global_store_dwordx4 v[32:33], v[176:179], off
	v_ashrrev_i32_e32 v37, 31, v36
	s_nop 0
	v_cvt_pk_bf16_f32 v168, v20, v21
	v_cvt_pk_bf16_f32 v169, v22, v23
	v_cvt_pk_bf16_f32 v170, v38, v39
	v_cvt_pk_bf16_f32 v171, v40, v41
	global_store_dwordx4 v[32:33], v[168:171], off offset:256
	s_nop 7
	v_mov_b32_e32 v16, v216
	v_mov_b32_e32 v17, v217
	v_mov_b32_e32 v18, v218
	v_mov_b32_e32 v19, v219
	v_mov_b32_e32 v20, v17
	v_mov_b32_e32 v21, v18
	v_mov_b32_e32 v17, v19
	v_pk_add_f32 v[16:17], v[20:21], v[16:17]
	s_nop 0
	v_add_f32_e32 v16, v16, v17
	v_fmamk_f32 v16, v16, 0x3c000000, v154
	v_mul_f32_e32 v17, 0x4f800000, v16
	v_cmp_gt_f32_e32 vcc, s77, v16
	s_nop 1
	v_cndmask_b32_e32 v18, v16, v17, vcc
	v_sqrt_f32_e32 v19, v18
	v_lshlrev_b64 v[16:17], 11, v[36:37]
	v_lshl_add_u64 v[16:17], s[44:45], 0, v[16:17]
	v_lshl_add_u64 v[16:17], v[16:17], 0, v[144:145]
	v_add_u32_e32 v20, -1, v19
	v_add_u32_e32 v21, 1, v19
	v_fma_f32 v22, -v20, v19, v18
	v_fma_f32 v23, -v21, v19, v18
	v_cmp_ge_f32_e64 s[6:7], 0, v22
	s_nop 1
	v_cndmask_b32_e64 v19, v19, v20, s[6:7]
	v_cmp_lt_f32_e64 s[6:7], 0, v23
	s_nop 1
	v_cndmask_b32_e64 v19, v19, v21, s[6:7]
	v_mul_f32_e32 v20, 0x37800000, v19
	v_cndmask_b32_e32 v19, v19, v20, vcc
	v_cmp_class_f32_e32 vcc, v18, v155
	s_nop 1
	v_cndmask_b32_e32 v18, v19, v18, vcc
	v_div_scale_f32 v19, s[6:7], v18, v18, 1.0
	v_rcp_f32_e32 v20, v19
	v_div_scale_f32 v21, vcc, 1.0, v18, 1.0
	v_fma_f32 v22, -v19, v20, 1.0
	v_fmac_f32_e32 v20, v22, v20
	v_mul_f32_e32 v22, v21, v20
	v_fma_f32 v23, -v19, v22, v21
	v_fmac_f32_e32 v22, v23, v20
	v_fma_f32 v19, -v19, v22, v21
	v_div_fmas_f32 v19, v19, v20, v22
	v_div_fixup_f32 v18, v19, v18, 1.0
	v_pk_mul_f32 v[14:15], v[14:15], v[18:19] op_sel_hi:[1,0]
	v_pk_mul_f32 v[12:13], v[12:13], v[18:19] op_sel_hi:[1,0]
	v_pk_mul_f32 v[10:11], v[10:11], v[18:19] op_sel_hi:[1,0]
	v_pk_mul_f32 v[8:9], v[8:9], v[18:19] op_sel_hi:[1,0]
	v_pk_mul_f32 v[6:7], v[6:7], v[18:19] op_sel_hi:[1,0]
	v_pk_mul_f32 v[4:5], v[4:5], v[18:19] op_sel_hi:[1,0]
	v_pk_mul_f32 v[20:21], v[2:3], v[18:19] op_sel_hi:[1,0]
	v_pk_mul_f32 v[18:19], v[0:1], v[18:19] op_sel_hi:[1,0]
	v_cvt_pk_bf16_f32 v180, v12, v13
	v_cvt_pk_bf16_f32 v181, v14, v15
	v_cvt_pk_bf16_f32 v182, v8, v9
	v_cvt_pk_bf16_f32 v183, v10, v11
	global_store_dwordx4 v[16:17], v[180:183], off
	s_and_b64 vcc, exec, s[4:5]
	s_mov_b64 s[4:5], -1
	v_cvt_pk_bf16_f32 v172, v4, v5
	v_cvt_pk_bf16_f32 v173, v6, v7
	v_cvt_pk_bf16_f32 v174, v18, v19
	v_cvt_pk_bf16_f32 v175, v20, v21
	global_store_dwordx4 v[16:17], v[172:175], off offset:256
	s_cbranch_vccnz .LBB0_341
	s_andn2_b64 vcc, exec, s[48:49]
	s_cbranch_vccnz .LBB0_340
	s_barrier
	s_branch .LBB0_340
